# hot loop heads (attention tile loop, four 8-phase GEMM loops, scan step) aligned to 64-byte instruction-fetch boundaries
# speedup vs baseline: 1.0061x; 1.0061x over previous
; #define PG8_LDA(dst, b, h) do { _Pragma("unroll") for (int m = 0; m < 4; ++m) _Pragma("unroll") for (int k = 0; k < 2; ++k) dst[m][k] = *(const LAS bf16x8*)(lds + PG8_SA(b, h) + aoff + m * 2048 + k * 1024); } while (0)
; template <class Epi>
; DI void gemm_phase(int wid0, LAS unsigned char* lds, const Gemm g, const StaticOrder& S, const Epi& E) {
;     ...
;         const bool has_next = S.next(ui + 1, nxt);
;         const char* nA = has_next ? (const char*)g.A + (size_t)nxt.pm * tstep : cA; const char* nB = has_next ? (const char*)g.Bt + (size_t)nxt.pn * tstep : cB;
;         for (int t = 0; t < nt; t += 2) {
;             const bool last = (t == nt - 2);
;             const char* a1 = cA + (size_t)(t + 1) * kstep;
;             const char* a2 = last ? nA : cA + (size_t)(t + 2) * kstep; const char* b2 = last ? nB : cB + (size_t)(t + 2) * kstep;
;             const char* a3 = a2 + kstep; const char* b3 = b2 + kstep;
;             PG8_LDB(B0, 0, 0); PG8_LDB(B1, 0, 1); PG8_SCHED; PG8_LDA(At, 0, 0); PG8_STAGE(PG8_SA(1, 1), a1 + hstep, voffA);
;             PG8_WAIT_V(8); PG8_WAIT_L(0); PG8_BAR; PG8_MMA(0, 0, At, B0); PG8_MMA(0, 1, At, B1); PG8_BAR; PG8_SCHED;
;             PG8_LDA(At, 0, 1); PG8_STAGE(PG8_SB(0, 0), b2, voffB); PG8_STAGE(PG8_SB(0, 1), b2 + hstep, voffB); PG8_STAGE(PG8_SA(0, 0), a2, voffA);
;             PG8_WAIT_V(8); PG8_WAIT_L(0); PG8_BAR; PG8_MMA(1, 0, At, B0); PG8_MMA(1, 1, At, B1); PG8_BAR; PG8_SCHED;
;             PG8_LDB(B0, 1, 0); PG8_LDB(B1, 1, 1); PG8_SCHED; PG8_LDA(At, 1, 0); PG8_STAGE(PG8_SA(0, 1), a2 + hstep, voffA);
;             PG8_WAIT_V(8); PG8_WAIT_L(0); PG8_BAR; PG8_MMA(0, 0, At, B0); PG8_MMA(0, 1, At, B1); PG8_BAR; PG8_SCHED;
;             PG8_LDA(At, 1, 1); PG8_STAGE(PG8_SB(1, 0), b3, voffB); PG8_STAGE(PG8_SB(1, 1), b3 + hstep, voffB); PG8_STAGE(PG8_SA(1, 0), a3, voffA);
;             PG8_WAIT_V(8); PG8_WAIT_L(0); PG8_BAR; PG8_MMA(1, 0, At, B0); PG8_MMA(1, 1, At, B1); PG8_BAR; PG8_SCHED;
;         }
;         if (wr == 0) PG8_BAR;
;         E(acc, cur, wr, wc, fr, fq);
;         if (!has_next) break;
; #pragma unroll
;         for (int a = 0; a < 2; ++a)
; #pragma unroll
;             for (int b = 0; b < 2; ++b)
; #pragma unroll
;                 for (int m = 0; m < 4; ++m)
; #pragma unroll
;                     for (int n = 0; n < 2; ++n) acc[a][b][m][n] = (f32x4){0.f, 0.f, 0.f, 0.f};
;         cur = nxt; cA = nA; cB = nB; ++ui;
.LBB0_57:
	s_ashr_i32 s15, s14, 31
	s_lshl_b64 s[16:17], s[14:15], 19
	s_add_u32 s16, s42, s16
	s_addc_u32 s17, s43, s17
	s_and_b64 s[18:19], s[38:39], exec
	s_cselect_b32 s15, s17, s23
	s_cselect_b32 s40, s16, s22
	s_ashr_i32 s13, s12, 31
	s_lshl_b64 s[18:19], s[12:13], 19
	s_add_u32 s18, s6, s18
	s_addc_u32 s19, s7, s19
	s_and_b64 s[66:67], s[38:39], exec
	s_cselect_b32 s13, s19, s69
	s_cselect_b32 s41, s18, s68
	s_add_u32 s22, s22, 0x40080
	s_addc_u32 s23, s23, 0
	s_add_u32 s66, s68, 0x100
	v_mov_b32_e32 v2, 0
	s_addc_u32 s67, s69, 0
	s_mov_b32 s79, -2
	v_mov_b32_e32 v3, v2
	v_mov_b32_e32 v4, v2
	v_mov_b32_e32 v5, v2
	v_mov_b32_e32 v6, v2
	v_mov_b32_e32 v7, v2
	v_mov_b32_e32 v8, v2
	v_mov_b32_e32 v9, v2
	v_mov_b32_e32 v18, v2
	v_mov_b32_e32 v19, v2
	v_mov_b32_e32 v20, v2
	v_mov_b32_e32 v21, v2
	v_mov_b32_e32 v22, v2
	v_mov_b32_e32 v23, v2
	v_mov_b32_e32 v24, v2
	v_mov_b32_e32 v25, v2
	v_mov_b32_e32 v34, v2
	v_mov_b32_e32 v35, v2
	v_mov_b32_e32 v36, v2
	v_mov_b32_e32 v37, v2
	v_mov_b32_e32 v38, v2
	v_mov_b32_e32 v39, v2
	v_mov_b32_e32 v40, v2
	v_mov_b32_e32 v41, v2
	v_mov_b32_e32 v50, v2
	v_mov_b32_e32 v51, v2
	v_mov_b32_e32 v52, v2
	v_mov_b32_e32 v53, v2
	v_mov_b32_e32 v54, v2
	v_mov_b32_e32 v55, v2
	v_mov_b32_e32 v56, v2
	v_mov_b32_e32 v57, v2
	v_mov_b32_e32 v10, v2
	v_mov_b32_e32 v11, v2
	v_mov_b32_e32 v12, v2
	v_mov_b32_e32 v13, v2
	v_mov_b32_e32 v14, v2
	v_mov_b32_e32 v15, v2
	v_mov_b32_e32 v16, v2
	v_mov_b32_e32 v17, v2
	v_mov_b32_e32 v26, v2
	v_mov_b32_e32 v27, v2
	v_mov_b32_e32 v28, v2
	v_mov_b32_e32 v29, v2
	v_mov_b32_e32 v30, v2
	v_mov_b32_e32 v31, v2
	v_mov_b32_e32 v32, v2
	v_mov_b32_e32 v33, v2
	v_mov_b32_e32 v42, v2
	v_mov_b32_e32 v43, v2
	v_mov_b32_e32 v44, v2
	v_mov_b32_e32 v45, v2
	v_mov_b32_e32 v46, v2
	v_mov_b32_e32 v47, v2
	v_mov_b32_e32 v48, v2
	v_mov_b32_e32 v49, v2
	v_mov_b32_e32 v58, v2
	v_mov_b32_e32 v59, v2
	v_mov_b32_e32 v60, v2
	v_mov_b32_e32 v61, v2
	v_mov_b32_e32 v62, v2
	v_mov_b32_e32 v63, v2
	v_mov_b32_e32 v64, v2
	v_mov_b32_e32 v65, v2
	v_mov_b32_e32 v66, v2
	v_mov_b32_e32 v67, v2
	v_mov_b32_e32 v68, v2
	v_mov_b32_e32 v69, v2
	v_mov_b32_e32 v70, v2
	v_mov_b32_e32 v71, v2
	v_mov_b32_e32 v72, v2
	v_mov_b32_e32 v73, v2
	v_mov_b32_e32 v82, v2
	v_mov_b32_e32 v83, v2
	v_mov_b32_e32 v84, v2
	v_mov_b32_e32 v85, v2
	v_mov_b32_e32 v86, v2
	v_mov_b32_e32 v87, v2
	v_mov_b32_e32 v88, v2
	v_mov_b32_e32 v89, v2
	v_mov_b32_e32 v98, v2
	v_mov_b32_e32 v99, v2
	v_mov_b32_e32 v100, v2
	v_mov_b32_e32 v101, v2
	v_mov_b32_e32 v102, v2
	v_mov_b32_e32 v103, v2
	v_mov_b32_e32 v104, v2
	v_mov_b32_e32 v105, v2
	v_mov_b32_e32 v114, v2
	v_mov_b32_e32 v115, v2
	v_mov_b32_e32 v116, v2
	v_mov_b32_e32 v117, v2
	v_mov_b32_e32 v118, v2
	v_mov_b32_e32 v119, v2
	v_mov_b32_e32 v120, v2
	v_mov_b32_e32 v121, v2
	v_mov_b32_e32 v74, v2
	v_mov_b32_e32 v75, v2
	v_mov_b32_e32 v76, v2
	v_mov_b32_e32 v77, v2
	v_mov_b32_e32 v78, v2
	v_mov_b32_e32 v79, v2
	v_mov_b32_e32 v80, v2
	v_mov_b32_e32 v81, v2
	v_mov_b32_e32 v90, v2
	v_mov_b32_e32 v91, v2
	v_mov_b32_e32 v92, v2
	v_mov_b32_e32 v93, v2
	v_mov_b32_e32 v94, v2
	v_mov_b32_e32 v95, v2
	v_mov_b32_e32 v96, v2
	v_mov_b32_e32 v97, v2
	v_mov_b32_e32 v106, v2
	v_mov_b32_e32 v107, v2
	v_mov_b32_e32 v108, v2
	v_mov_b32_e32 v109, v2
	v_mov_b32_e32 v110, v2
	v_mov_b32_e32 v111, v2
	v_mov_b32_e32 v112, v2
	v_mov_b32_e32 v113, v2
	v_mov_b32_e32 v122, v2
	v_mov_b32_e32 v123, v2
	v_mov_b32_e32 v124, v2
	v_mov_b32_e32 v125, v2
	v_mov_b32_e32 v126, v2
	v_mov_b32_e32 v127, v2
	v_mov_b32_e32 v128, v2
	v_mov_b32_e32 v129, v2
	.p2align	6

; DI void phase_attn(int wid0, const Params& p, int L, unsigned char* lds, bool dry) {
;     ...
;         { const int row = 4 * wid + (lane >> 4), gsrc = (lane & 15) ^ (row & 7); koff = (unsigned)(row * 2048 + 8 * gsrc) * 2u;
;           const int w5 = (lane & 31) >> 2, kl = (w5 & 3) + 8 * (w5 >> 2) + 4 * (wid >> 2), col = ((2 * wid + (lane >> 5)) & 7) * 32 + (lane & 3) * 8; voff = (unsigned)(kl * 2048 + col) * 2u; }
;         if (G == 256) {
;             if (ui < 8) { const int bh = 8 * ui + (blk & 7), j = blk >> 3; qb = (ui & 1) ? j : 31 - j; b = bh >> 3; hh = bh & 7; }
;             else if (ui == 8 && blk < 8) { meta = true; hh = blk; b = 0; qb = 0; }
;             else break;
;         } else {
;             const int u = blk + ui * G;
;             if (u < 2048) { const int bh = u & 63; qb = 31 - (u >> 6); b = bh >> 3; hh = bh & 7; }
;             else if (u < 2056) { meta = true; hh = u - 2048; b = 0; qb = 0; }
;             else break;
;         }
;         const int qrow0 = meta ? MREG : b * 4096 + 128 * qb, qpos0 = meta ? 0 : 16 + 128 * qb, ntiles = meta ? 1 : 1 + 4 * (qb + 1);
;         if (tid < 130) tab[tid] = (tid < 129) ? biasT[hh * 129 + tid] : -__builtin_inff();
;         int myrow = qrow0 + 32 * rg + r32; if (meta && myrow > MREG + 63) myrow = MREG + 63;
;         const bf16_t* qp = qbuf + (size_t)myrow * 2048 + hh * 256 + psub * 128 + hi * 8;
;         unsigned char* qlds = lds + wid * 8192 + lane * 16;
; #pragma unroll
;         for (int d0 = 0; d0 < 8; ++d0) *(bf16x8*)(qlds + d0 * 1024) = *(const bf16x8*)(qp + d0 * 16);
;         const int wq0 = qpos0 + 32 * rg, qpos = wq0 + r32;
;         const float bfar = biasT[hh * 129 + 128];
;         const bf16_t* kh_ = kbuf + hh * 256; const bf16_t* vh_ = vbuf + hh * 256;
;         attn_stage(kh_ + (size_t)MREG * 2048, vh_ + (size_t)MREG * 2048, koff, voff, ldsl + 65536, wid);
.LBB0_97:
	s_or_b64 exec, exec, s[10:11]
	v_subrev_u32_e32 v2, s37, v191
	v_lshrrev_b32_e32 v2, 2, v2
	v_cmp_gt_u32_e32 vcc, 0xfc, v2
	s_mov_b64 s[10:11], vcc
	v_cmp_gt_u32_e32 vcc, 62, v2
	v_add_u32_e32 v2, 0xffffffc2, v2
	v_max_i32_e32 v2, 0, v2
	v_min_i32_e32 v2, 0x80, v2
	v_add_u32_e32 v2, s8, v2
	v_mov_b32_e32 v3, 0
	v_readlane_b32 s6, v245, 40
	v_readlane_b32 s7, v245, 41
	s_mov_b64 s[12:13], exec
	s_nop 1
	v_lshl_add_u64 v[2:3], v[2:3], 2, s[6:7]
	s_and_b64 exec, exec, s[10:11]
	global_load_dword v0, v[2:3], off
	v_mov_b32_e32 v3, 0xff800000
	s_waitcnt vmcnt(0)
	v_cndmask_b32_e32 v0, v0, v3, vcc
	ds_write_b32 v191, v0 offset:3328
	s_mov_b64 exec, s[12:13]
	s_lshl_b32 s40, s73, 12
	s_lshl_b32 s10, s75, 7
	s_add_i32 s9, s40, s10
	s_and_b64 s[6:7], s[76:77], exec
	s_cselect_b32 s71, 0x8000, s9
	s_lshl_b32 s6, s75, 2
	s_add_i32 s9, s6, 5
	s_and_b64 s[6:7], s[76:77], exec
	v_ashrrev_i32_e32 v0, 4, v4
	v_readlane_b32 s7, v245, 61
	v_and_b32_e32 v2, 15, v4
	v_lshrrev_b32_e32 v3, 1, v4
	v_add_u32_e32 v0, s7, v0
	v_bitop3_b32 v2, v0, v2, 15 bitop3:0x6c
	v_lshlrev_b32_e32 v0, 12, v0
	v_lshl_or_b32 v0, v2, 4, v0
	v_lshrrev_b32_e32 v2, 2, v4
	v_and_b32_e32 v3, 8, v3
	v_readlane_b32 s7, v245, 63
	v_and_or_b32 v2, v2, 3, v3
	v_lshlrev_b32_e32 v8, 3, v4
	v_add_u32_e32 v3, s7, v4
	v_readlane_b32 s7, v244, 1
	v_and_b32_e32 v7, 31, v4
	v_and_b32_e32 v3, 0xe0, v3
	v_and_b32_e32 v5, 24, v8
	v_lshl_add_u32 v2, v2, 11, s7
	v_or3_b32 v2, v2, v3, v5
	v_or_b32_e32 v3, s41, v7
	v_or_b32_e32 v3, s71, v3
	v_min_i32_e32 v9, 0x803f, v3
	v_cndmask_b32_e64 v10, v3, v9, s[76:77]
	s_cselect_b32 s6, 1, s9
	v_ashrrev_i32_e32 v11, 31, v10
	s_lshl_b32 s12, s49, 8
	v_lshlrev_b64 v[10:11], 12, v[10:11]
	s_ashr_i32 s13, s12, 31
	v_ashrrev_i32_e32 v6, 5, v4
	v_lshl_add_u64 v[10:11], s[0:1], 0, v[10:11]
	s_lshl_b64 s[78:79], s[12:13], 1
	v_readlane_b32 s12, v244, 5
	v_lshl_add_u64 v[10:11], v[10:11], 0, s[78:79]
	v_readlane_b32 s13, v244, 6
	v_lshlrev_b32_e32 v12, 3, v6
	v_ashrrev_i32_e32 v13, 31, v12
	v_lshl_add_u64 v[10:11], s[12:13], 1, v[10:11]
	v_lshl_add_u64 v[14:15], v[12:13], 1, v[10:11]
	global_load_dwordx4 v[248:251], v[14:15], off
	s_ashr_i32 s9, s8, 31
	s_lshl_b64 s[8:9], s[8:9], 2
	v_readlane_b32 s12, v245, 40
	v_lshlrev_b32_e32 v9, 4, v4
	v_readlane_b32 s7, v244, 7
	v_readlane_b32 s13, v245, 41
	s_add_u32 s8, s12, s8
	s_addc_u32 s9, s13, s9
	global_load_dword v176, v1, s[8:9] offset:512
	s_add_u32 s12, s28, s78
	s_addc_u32 s13, s29, s79
	s_mov_b64 s[84:85], s[12:13]
	v_readlane_b32 s8, v245, 38
	v_readlane_b32 s9, v245, 39
	s_add_u32 s8, s8, s78
	v_readlane_b32 s7, v244, 9
	s_addc_u32 s9, s9, s79
	s_mov_b64 s[86:87], s[8:9]
	v_lshl_add_u64 v[178:179], s[12:13], 0, v[0:1]
	v_mov_b32_e32 v131, v0
	s_mov_b64 s[14:15], 0x8000000
	s_add_i32 s7, s7, 0
	v_lshlrev_b32_e32 v2, 1, v2
	s_add_i32 m0, s7, 0x10000
	s_mov_b64 s[12:13], 0x8000100
	v_mov_b32_e32 v3, v1
	v_lshl_add_u64 v[180:181], s[8:9], 0, v[2:3]
	v_mov_b32_e32 v208, v2
	v_lshl_add_u64 v[2:3], v[180:181], 0, s[14:15]
	s_mov_b64 s[8:9], 0x8010000
	global_load_dwordx4 v[252:255], v[14:15], off offset:32
	global_load_dwordx4 v[200:203], v[14:15], off offset:64
	global_load_dwordx4 v[204:207], v[14:15], off offset:96
	global_load_dwordx4 v[164:167], v[14:15], off offset:128
	global_load_dwordx4 v[168:171], v[14:15], off offset:160
	global_load_dwordx4 v[172:175], v[14:15], off offset:192
	global_load_dwordx4 v[232:235], v[14:15], off offset:224
	v_lshl_add_u64 v[10:11], v[178:179], 0, s[14:15]
	global_load_lds_dwordx4 v[10:11], off
	v_lshl_add_u64 v[10:11], v[178:179], 0, s[12:13]
	s_add_i32 m0, s7, 0x12000
	s_nop 0
	global_load_lds_dwordx4 v[10:11], off
	s_add_i32 m0, s7, 0x0
	s_nop 0
	global_load_lds_dwordx4 v[2:3], off
	v_lshl_add_u64 v[2:3], v[180:181], 0, s[8:9]
	s_add_i32 m0, s7, 0x2000
	s_mov_b32 s7, 0
	global_load_lds_dwordx4 v[2:3], off
	s_cmp_lt_i32 s6, 1
	s_cbranch_scc1 .LBB0_114
; DI void phase_attn(int wid0, const Params& p, int L, unsigned char* lds, bool dry) {
;     ...
;         f32x16 o[8];
; #pragma unroll
;         for (int d = 0; d < 8; ++d)
; #pragma unroll
;             for (int r = 0; r < 16; ++r) o[d][r] = 0.f;
;         float m_reg = -1e30f, l_reg = 0.f;
;         for (int t = 0; t < ntiles; ++t) {
;             asm volatile("s_waitcnt vmcnt(0) lgkmcnt(0)" ::: "memory"); __builtin_amdgcn_s_barrier(); asm volatile("" ::: "memory");
;             if (t + 1 < ntiles) attn_stage(kh_ + (size_t)(b * 4096 + 32 * t) * 2048, vh_ + (size_t)(b * 4096 + 32 * t) * 2048, koff, voff, ldsl + 65536 + ((t + 1) & 1) * 32768, wid);
;             const int kpos0 = (t == 0) ? 0 : 16 + 32 * (t - 1);
;             if (kpos0 <= wq0 + 31) {
;                 const unsigned char* Ks = lds + 65536 + (t & 1) * 32768 + psub * 8192;
;                 f32x16 p0, p0b;
; #pragma unroll
;                 for (int r = 0; r < 16; ++r) { p0[r] = 0.f; p0b[r] = 0.f; }
;                 int swz = (r32 & 6) << 4, kro = r32 * 256 + ((hi ^ (r32 & 1)) << 4); asm volatile("" : "+v"(swz), "+v"(kro));
; #pragma unroll
	s_or_b32 s10, s10, 16
	v_lshlrev_b32_e32 v0, 8, v7
	v_bitop3_b32 v2, v6, v4, 1 bitop3:0x78
	s_and_b64 s[8:9], s[76:77], exec
	v_lshl_add_u32 v193, v2, 4, v0
	v_lshlrev_b32_e32 v2, 1, v4
	s_cselect_b32 s39, 0, s10
	v_and_b32_e32 v0, 0xc0, v9
	v_and_b32_e32 v2, 32, v2
	v_readlane_b32 s48, v244, 17
	s_or_b32 s8, s39, s41
	v_and_b32_e32 v3, 0x100, v8
	v_add3_u32 v0, s48, v0, v2
	v_mov_b32_e32 v14, v1
	v_mov_b32_e32 v15, v1
	s_add_i32 s38, s8, 31
	v_and_b32_e32 v192, 0xe0, v9
	v_lshlrev_b32_e32 v194, 2, v6
	v_add_u32_e32 v195, s8, v7
	v_cmp_gt_u32_e64 s[8:9], 32, v4
	v_lshl_add_u32 v196, v7, 2, s2
	v_lshlrev_b32_e32 v16, 4, v6
	v_cmp_gt_i32_e64 s[10:11], 4, v6
	v_cmp_gt_i32_e64 s[18:19], 2, v6
	v_cmp_gt_i32_e64 s[20:21], 0, v6
	v_cmp_gt_i32_e64 s[22:23], -2, v6
	v_add3_u32 v212, v0, v3, v5
	v_add_u32_e32 v212, 0xffff0000, v212
	v_mov_b32_e32 v0, v1
	v_mov_b32_e32 v2, v1
	v_mov_b32_e32 v3, v1
	v_mov_b32_e32 v4, v1
	v_mov_b32_e32 v5, v1
	v_mov_b32_e32 v6, v1
	v_mov_b32_e32 v7, v1
	v_mov_b32_e32 v8, v1
	v_mov_b32_e32 v9, v1
	v_mov_b32_e32 v10, v1
	v_mov_b32_e32 v11, v1
	v_mov_b32_e32 v12, v1
	v_mov_b32_e32 v13, v1
	v_mov_b64_e32 v[128:129], v[14:15]
	v_mov_b64_e32 v[112:113], v[14:15]
	v_mov_b64_e32 v[96:97], v[14:15]
	v_mov_b64_e32 v[80:81], v[14:15]
	v_mov_b64_e32 v[64:65], v[14:15]
	v_mov_b64_e32 v[48:49], v[14:15]
	v_mov_b64_e32 v[32:33], v[14:15]
	v_or_b32_e32 v197, 1, v194
	v_or_b32_e32 v198, 2, v194
	v_or_b32_e32 v199, 3, v194
	v_readlane_b32 s48, v244, 19
	v_add_u32_e32 v214, s2, v16
	v_mov_b64_e32 v[126:127], v[12:13]
	v_mov_b64_e32 v[124:125], v[10:11]
	v_mov_b64_e32 v[122:123], v[8:9]
	v_mov_b64_e32 v[120:121], v[6:7]
	v_mov_b64_e32 v[118:119], v[4:5]
	v_mov_b64_e32 v[116:117], v[2:3]
	v_mov_b64_e32 v[114:115], v[0:1]
	v_mov_b64_e32 v[110:111], v[12:13]
	v_mov_b64_e32 v[108:109], v[10:11]
	v_mov_b64_e32 v[106:107], v[8:9]
	v_mov_b64_e32 v[104:105], v[6:7]
	v_mov_b64_e32 v[102:103], v[4:5]
	v_mov_b64_e32 v[100:101], v[2:3]
	v_mov_b64_e32 v[98:99], v[0:1]
	v_mov_b64_e32 v[94:95], v[12:13]
	v_mov_b64_e32 v[92:93], v[10:11]
	v_mov_b64_e32 v[90:91], v[8:9]
	v_mov_b64_e32 v[88:89], v[6:7]
	v_mov_b64_e32 v[86:87], v[4:5]
	v_mov_b64_e32 v[84:85], v[2:3]
	v_mov_b64_e32 v[82:83], v[0:1]
	v_mov_b64_e32 v[78:79], v[12:13]
	v_mov_b64_e32 v[76:77], v[10:11]
	v_mov_b64_e32 v[74:75], v[8:9]
	v_mov_b64_e32 v[72:73], v[6:7]
	v_mov_b64_e32 v[70:71], v[4:5]
	v_mov_b64_e32 v[68:69], v[2:3]
	v_mov_b64_e32 v[66:67], v[0:1]
	v_mov_b64_e32 v[62:63], v[12:13]
	v_mov_b64_e32 v[60:61], v[10:11]
	v_mov_b64_e32 v[58:59], v[8:9]
	v_mov_b64_e32 v[56:57], v[6:7]
	v_mov_b64_e32 v[54:55], v[4:5]
	v_mov_b64_e32 v[52:53], v[2:3]
	v_mov_b64_e32 v[50:51], v[0:1]
	v_mov_b64_e32 v[46:47], v[12:13]
	v_mov_b64_e32 v[44:45], v[10:11]
	v_mov_b64_e32 v[42:43], v[8:9]
	v_mov_b64_e32 v[40:41], v[6:7]
	v_mov_b64_e32 v[38:39], v[4:5]
	v_mov_b64_e32 v[36:37], v[2:3]
	v_mov_b64_e32 v[34:35], v[0:1]
	v_mov_b64_e32 v[30:31], v[12:13]
	v_mov_b64_e32 v[28:29], v[10:11]
	v_mov_b64_e32 v[26:27], v[8:9]
	v_mov_b64_e32 v[24:25], v[6:7]
	v_mov_b64_e32 v[22:23], v[4:5]
	v_mov_b64_e32 v[20:21], v[2:3]
	v_mov_b64_e32 v[18:19], v[0:1]
	v_mov_b64_e32 v[16:17], v[14:15]
	v_cmp_gt_i32_e64 s[12:13], 16, v197
	v_cmp_gt_i32_e64 s[14:15], 16, v198
	v_cmp_gt_i32_e64 s[16:17], 16, v199
	s_waitcnt vmcnt(11)
	v_mov_b32_e32 v182, v176
	v_mov_b32_e32 v183, v176
	s_add_i32 s39, s48, s39
	v_mov_b32_e32 v130, 0
	v_mov_b32_e32 v213, 0xf149f2ca
	s_mov_b32 s66, 0
	s_mov_b32 s100, 0x100
	v_readlane_b32 s80, v244, 13
	s_and_b32 s80, s80, 0x800
	s_or_b32 s100, s100, s80
	v_add_u32_e32 v182, 0x10000, v131
	v_add_u32_e32 v183, 0x4000, v208
	s_mov_b32 s67, 1
	s_mov_b32 s7, -16
	s_mov_b32 s97, 0x4138aa3b
	s_mov_b32 s80, s40
	s_mov_b32 s81, 0
	s_lshl_b64 s[80:81], s[80:81], 12
	s_add_u32 s88, s84, s80
	s_addc_u32 s89, s85, s81
	s_add_u32 s92, s86, s80
	s_addc_u32 s93, s87, s81
	s_add_u32 s94, s92, 0x10000
	s_addc_u32 s95, s93, 0
	s_add_u32 s90, s88, 0x100
	s_addc_u32 s91, s89, 0
	s_add_i32 s96, s4, 0xffff0000
	v_mov_b32_e32 v132, 0
	v_mov_b32_e32 v133, 0
	v_mov_b32_e32 v134, 0
	v_mov_b32_e32 v135, 0
	v_mov_b32_e32 v136, 0
	v_mov_b32_e32 v137, 0
	v_mov_b32_e32 v138, 0
	v_mov_b32_e32 v139, 0
	s_lshl_b32 s80, s96, 1
	s_add_i32 s80, s80, 0xc000
	v_lshl_add_u32 v226, v190, 4, s80
	ds_write_b128 v226, v[132:135]
	ds_write_b128 v226, v[132:135] offset:1024
	v_add_u32_e32 v226, s5, v193
	v_add_u32_e32 v188, v226, v192
	v_xad_u32 v177, v192, 32, v226
	v_xad_u32 v209, v192, 64, v226
	s_movk_i32 s80, 0x60
	v_xad_u32 v210, v192, s80, v226
	s_movk_i32 s80, 0x80
	v_xad_u32 v211, v192, s80, v226
	s_movk_i32 s80, 0xa0
	v_xad_u32 v215, v192, s80, v226
	s_movk_i32 s80, 0xc0
	v_xad_u32 v224, v192, s80, v226
	s_movk_i32 s80, 0xe0
	v_xad_u32 v225, v192, s80, v226
	v_mov_b64_e32 v[14:15], v[12:13]
	v_mov_b64_e32 v[12:13], v[10:11]
	v_mov_b64_e32 v[10:11], v[8:9]
	v_mov_b64_e32 v[8:9], v[6:7]
	v_mov_b64_e32 v[6:7], v[4:5]
	v_mov_b64_e32 v[4:5], v[2:3]
	v_mov_b64_e32 v[2:3], v[0:1]
	s_mov_b32 s69, 0
	.p2align	6

; #define PG8_LDA(dst, b, h) do { _Pragma("unroll") for (int m = 0; m < 4; ++m) _Pragma("unroll") for (int k = 0; k < 2; ++k) dst[m][k] = *(const LAS bf16x8*)(lds + PG8_SA(b, h) + aoff + m * 2048 + k * 1024); } while (0)
; template <class Epi>
; DI void gemm_phase(int wid0, LAS unsigned char* lds, const Gemm g, const StaticOrder& S, const Epi& E) {
;     ...
;         const bool has_next = S.next(ui + 1, nxt);
;         const char* nA = has_next ? (const char*)g.A + (size_t)nxt.pm * tstep : cA; const char* nB = has_next ? (const char*)g.Bt + (size_t)nxt.pn * tstep : cB;
;         for (int t = 0; t < nt; t += 2) {
;             const bool last = (t == nt - 2);
;             const char* a1 = cA + (size_t)(t + 1) * kstep;
;             const char* a2 = last ? nA : cA + (size_t)(t + 2) * kstep; const char* b2 = last ? nB : cB + (size_t)(t + 2) * kstep;
;             const char* a3 = a2 + kstep; const char* b3 = b2 + kstep;
;             PG8_LDB(B0, 0, 0); PG8_LDB(B1, 0, 1); PG8_SCHED; PG8_LDA(At, 0, 0); PG8_STAGE(PG8_SA(1, 1), a1 + hstep, voffA);
;             PG8_WAIT_V(8); PG8_WAIT_L(0); PG8_BAR; PG8_MMA(0, 0, At, B0); PG8_MMA(0, 1, At, B1); PG8_BAR; PG8_SCHED;
;             PG8_LDA(At, 0, 1); PG8_STAGE(PG8_SB(0, 0), b2, voffB); PG8_STAGE(PG8_SB(0, 1), b2 + hstep, voffB); PG8_STAGE(PG8_SA(0, 0), a2, voffA);
;             PG8_WAIT_V(8); PG8_WAIT_L(0); PG8_BAR; PG8_MMA(1, 0, At, B0); PG8_MMA(1, 1, At, B1); PG8_BAR; PG8_SCHED;
;             PG8_LDB(B0, 1, 0); PG8_LDB(B1, 1, 1); PG8_SCHED; PG8_LDA(At, 1, 0); PG8_STAGE(PG8_SA(0, 1), a2 + hstep, voffA);
;             PG8_WAIT_V(8); PG8_WAIT_L(0); PG8_BAR; PG8_MMA(0, 0, At, B0); PG8_MMA(0, 1, At, B1); PG8_BAR; PG8_SCHED;
;             PG8_LDA(At, 1, 1); PG8_STAGE(PG8_SB(1, 0), b3, voffB); PG8_STAGE(PG8_SB(1, 1), b3 + hstep, voffB); PG8_STAGE(PG8_SA(1, 0), a3, voffA);
;             PG8_WAIT_V(8); PG8_WAIT_L(0); PG8_BAR; PG8_MMA(1, 0, At, B0); PG8_MMA(1, 1, At, B1); PG8_BAR; PG8_SCHED;
;         }
;         if (wr == 0) PG8_BAR;
;         E(acc, cur, wr, wc, fr, fq);
;         if (!has_next) break;
; #pragma unroll
;         for (int a = 0; a < 2; ++a)
; #pragma unroll
;             for (int b = 0; b < 2; ++b)
; #pragma unroll
;                 for (int m = 0; m < 4; ++m)
; #pragma unroll
;                     for (int n = 0; n < 2; ++n) acc[a][b][m][n] = (f32x4){0.f, 0.f, 0.f, 0.f};
;         cur = nxt; cA = nA; cB = nB; ++ui;
.LBB0_138:
	s_ashr_i32 s15, s14, 31
	s_lshl_b64 s[16:17], s[14:15], 19
	s_add_u32 s16, s42, s16
	s_addc_u32 s17, s43, s17
	s_and_b64 s[18:19], s[4:5], exec
	s_cselect_b32 s15, s17, s21
	s_cselect_b32 s66, s16, s20
	s_ashr_i32 s13, s12, 31
	s_lshl_b64 s[18:19], s[12:13], 19
	v_readlane_b32 s38, v245, 44
	v_readlane_b32 s39, v245, 45
	s_add_u32 s18, s38, s18
	s_addc_u32 s19, s39, s19
	s_and_b64 s[38:39], s[4:5], exec
	s_cselect_b32 s13, s19, s23
	s_cselect_b32 s67, s18, s22
	s_add_u32 s20, s20, 0x40080
	s_addc_u32 s21, s21, 0
	s_add_u32 s69, s22, 0x100
	v_mov_b32_e32 v2, 0
	s_addc_u32 s70, s23, 0
	s_mov_b32 s71, -2
	v_mov_b32_e32 v3, v2
	v_mov_b32_e32 v4, v2
	v_mov_b32_e32 v5, v2
	v_mov_b32_e32 v6, v2
	v_mov_b32_e32 v7, v2
	v_mov_b32_e32 v8, v2
	v_mov_b32_e32 v9, v2
	v_mov_b32_e32 v10, v2
	v_mov_b32_e32 v11, v2
	v_mov_b32_e32 v12, v2
	v_mov_b32_e32 v13, v2
	v_mov_b32_e32 v14, v2
	v_mov_b32_e32 v15, v2
	v_mov_b32_e32 v16, v2
	v_mov_b32_e32 v17, v2
	v_mov_b32_e32 v26, v2
	v_mov_b32_e32 v27, v2
	v_mov_b32_e32 v28, v2
	v_mov_b32_e32 v29, v2
	v_mov_b32_e32 v30, v2
	v_mov_b32_e32 v31, v2
	v_mov_b32_e32 v32, v2
	v_mov_b32_e32 v33, v2
	v_mov_b32_e32 v42, v2
	v_mov_b32_e32 v43, v2
	v_mov_b32_e32 v44, v2
	v_mov_b32_e32 v45, v2
	v_mov_b32_e32 v46, v2
	v_mov_b32_e32 v47, v2
	v_mov_b32_e32 v48, v2
	v_mov_b32_e32 v49, v2
	v_mov_b32_e32 v18, v2
	v_mov_b32_e32 v19, v2
	v_mov_b32_e32 v20, v2
	v_mov_b32_e32 v21, v2
	v_mov_b32_e32 v22, v2
	v_mov_b32_e32 v23, v2
	v_mov_b32_e32 v24, v2
	v_mov_b32_e32 v25, v2
	v_mov_b32_e32 v34, v2
	v_mov_b32_e32 v35, v2
	v_mov_b32_e32 v36, v2
	v_mov_b32_e32 v37, v2
	v_mov_b32_e32 v38, v2
	v_mov_b32_e32 v39, v2
	v_mov_b32_e32 v40, v2
	v_mov_b32_e32 v41, v2
	v_mov_b32_e32 v50, v2
	v_mov_b32_e32 v51, v2
	v_mov_b32_e32 v52, v2
	v_mov_b32_e32 v53, v2
	v_mov_b32_e32 v54, v2
	v_mov_b32_e32 v55, v2
	v_mov_b32_e32 v56, v2
	v_mov_b32_e32 v57, v2
	v_mov_b32_e32 v58, v2
	v_mov_b32_e32 v59, v2
	v_mov_b32_e32 v60, v2
	v_mov_b32_e32 v61, v2
	v_mov_b32_e32 v62, v2
	v_mov_b32_e32 v63, v2
	v_mov_b32_e32 v64, v2
	v_mov_b32_e32 v65, v2
	v_mov_b32_e32 v66, v2
	v_mov_b32_e32 v67, v2
	v_mov_b32_e32 v68, v2
	v_mov_b32_e32 v69, v2
	v_mov_b32_e32 v70, v2
	v_mov_b32_e32 v71, v2
	v_mov_b32_e32 v72, v2
	v_mov_b32_e32 v73, v2
	v_mov_b32_e32 v74, v2
	v_mov_b32_e32 v75, v2
	v_mov_b32_e32 v76, v2
	v_mov_b32_e32 v77, v2
	v_mov_b32_e32 v78, v2
	v_mov_b32_e32 v79, v2
	v_mov_b32_e32 v80, v2
	v_mov_b32_e32 v81, v2
	v_mov_b32_e32 v90, v2
	v_mov_b32_e32 v91, v2
	v_mov_b32_e32 v92, v2
	v_mov_b32_e32 v93, v2
	v_mov_b32_e32 v94, v2
	v_mov_b32_e32 v95, v2
	v_mov_b32_e32 v96, v2
	v_mov_b32_e32 v97, v2
	v_mov_b32_e32 v106, v2
	v_mov_b32_e32 v107, v2
	v_mov_b32_e32 v108, v2
	v_mov_b32_e32 v109, v2
	v_mov_b32_e32 v110, v2
	v_mov_b32_e32 v111, v2
	v_mov_b32_e32 v112, v2
	v_mov_b32_e32 v113, v2
	v_mov_b32_e32 v82, v2
	v_mov_b32_e32 v83, v2
	v_mov_b32_e32 v84, v2
	v_mov_b32_e32 v85, v2
	v_mov_b32_e32 v86, v2
	v_mov_b32_e32 v87, v2
	v_mov_b32_e32 v88, v2
	v_mov_b32_e32 v89, v2
	v_mov_b32_e32 v98, v2
	v_mov_b32_e32 v99, v2
	v_mov_b32_e32 v100, v2
	v_mov_b32_e32 v101, v2
	v_mov_b32_e32 v102, v2
	v_mov_b32_e32 v103, v2
	v_mov_b32_e32 v104, v2
	v_mov_b32_e32 v105, v2
	v_mov_b32_e32 v114, v2
	v_mov_b32_e32 v115, v2
	v_mov_b32_e32 v116, v2
	v_mov_b32_e32 v117, v2
	v_mov_b32_e32 v118, v2
	v_mov_b32_e32 v119, v2
	v_mov_b32_e32 v120, v2
	v_mov_b32_e32 v121, v2
	v_mov_b32_e32 v122, v2
	v_mov_b32_e32 v123, v2
	v_mov_b32_e32 v124, v2
	v_mov_b32_e32 v125, v2
	v_mov_b32_e32 v126, v2
	v_mov_b32_e32 v127, v2
	v_mov_b32_e32 v128, v2
	v_mov_b32_e32 v129, v2
	.p2align	6

; #define PG8_LDA(dst, b, h) do { _Pragma("unroll") for (int m = 0; m < 4; ++m) _Pragma("unroll") for (int k = 0; k < 2; ++k) dst[m][k] = *(const LAS bf16x8*)(lds + PG8_SA(b, h) + aoff + m * 2048 + k * 1024); } while (0)
; template <class Epi>
; DI void gemm_phase(int wid0, LAS unsigned char* lds, const Gemm g, const StaticOrder& S, const Epi& E) {
;     ...
;         const bool has_next = S.next(ui + 1, nxt);
;         const char* nA = has_next ? (const char*)g.A + (size_t)nxt.pm * tstep : cA; const char* nB = has_next ? (const char*)g.Bt + (size_t)nxt.pn * tstep : cB;
;         for (int t = 0; t < nt; t += 2) {
;             const bool last = (t == nt - 2);
;             const char* a1 = cA + (size_t)(t + 1) * kstep;
;             const char* a2 = last ? nA : cA + (size_t)(t + 2) * kstep; const char* b2 = last ? nB : cB + (size_t)(t + 2) * kstep;
;             const char* a3 = a2 + kstep; const char* b3 = b2 + kstep;
;             PG8_LDB(B0, 0, 0); PG8_LDB(B1, 0, 1); PG8_SCHED; PG8_LDA(At, 0, 0); PG8_STAGE(PG8_SA(1, 1), a1 + hstep, voffA);
;             PG8_WAIT_V(8); PG8_WAIT_L(0); PG8_BAR; PG8_MMA(0, 0, At, B0); PG8_MMA(0, 1, At, B1); PG8_BAR; PG8_SCHED;
;             PG8_LDA(At, 0, 1); PG8_STAGE(PG8_SB(0, 0), b2, voffB); PG8_STAGE(PG8_SB(0, 1), b2 + hstep, voffB); PG8_STAGE(PG8_SA(0, 0), a2, voffA);
;             PG8_WAIT_V(8); PG8_WAIT_L(0); PG8_BAR; PG8_MMA(1, 0, At, B0); PG8_MMA(1, 1, At, B1); PG8_BAR; PG8_SCHED;
;             PG8_LDB(B0, 1, 0); PG8_LDB(B1, 1, 1); PG8_SCHED; PG8_LDA(At, 1, 0); PG8_STAGE(PG8_SA(0, 1), a2 + hstep, voffA);
;             PG8_WAIT_V(8); PG8_WAIT_L(0); PG8_BAR; PG8_MMA(0, 0, At, B0); PG8_MMA(0, 1, At, B1); PG8_BAR; PG8_SCHED;
;             PG8_LDA(At, 1, 1); PG8_STAGE(PG8_SB(1, 0), b3, voffB); PG8_STAGE(PG8_SB(1, 1), b3 + hstep, voffB); PG8_STAGE(PG8_SA(1, 0), a3, voffA);
;             PG8_WAIT_V(8); PG8_WAIT_L(0); PG8_BAR; PG8_MMA(1, 0, At, B0); PG8_MMA(1, 1, At, B1); PG8_BAR; PG8_SCHED;
;         }
;         if (wr == 0) PG8_BAR;
;         E(acc, cur, wr, wc, fr, fq);
;         if (!has_next) break;
; #pragma unroll
;         for (int a = 0; a < 2; ++a)
; #pragma unroll
;             for (int b = 0; b < 2; ++b)
; #pragma unroll
;                 for (int m = 0; m < 4; ++m)
; #pragma unroll
;                     for (int n = 0; n < 2; ++n) acc[a][b][m][n] = (f32x4){0.f, 0.f, 0.f, 0.f};
;         cur = nxt; cA = nA; cB = nB; ++ui;
.LBB0_206:
	s_ashr_i32 s19, s18, 31
	s_lshl_b64 s[20:21], s[18:19], 20
	s_add_u32 s20, s8, s20
	s_addc_u32 s21, s9, s21
	s_and_b64 s[22:23], s[4:5], exec
	s_cselect_b32 s19, s21, s45
	s_cselect_b32 s66, s20, s44
	s_ashr_i32 s17, s16, 31
	s_lshl_b64 s[22:23], s[16:17], 20
	s_add_u32 s22, s26, s22
	s_addc_u32 s23, s27, s23
	s_and_b64 s[48:49], s[4:5], exec
	s_cselect_b32 s17, s23, s47
	s_cselect_b32 s67, s22, s46
	s_add_u32 s44, s44, 0x80080
	s_addc_u32 s45, s45, 0
	s_add_u32 s69, s46, 0x100
	v_mov_b32_e32 v2, 0
	s_addc_u32 s70, s47, 0
	s_mov_b32 s71, -2
	v_mov_b32_e32 v3, v2
	v_mov_b32_e32 v4, v2
	v_mov_b32_e32 v5, v2
	v_mov_b32_e32 v6, v2
	v_mov_b32_e32 v7, v2
	v_mov_b32_e32 v8, v2
	v_mov_b32_e32 v9, v2
	v_mov_b32_e32 v18, v2
	v_mov_b32_e32 v19, v2
	v_mov_b32_e32 v20, v2
	v_mov_b32_e32 v21, v2
	v_mov_b32_e32 v22, v2
	v_mov_b32_e32 v23, v2
	v_mov_b32_e32 v24, v2
	v_mov_b32_e32 v25, v2
	v_mov_b32_e32 v34, v2
	v_mov_b32_e32 v35, v2
	v_mov_b32_e32 v36, v2
	v_mov_b32_e32 v37, v2
	v_mov_b32_e32 v38, v2
	v_mov_b32_e32 v39, v2
	v_mov_b32_e32 v40, v2
	v_mov_b32_e32 v41, v2
	v_mov_b32_e32 v50, v2
	v_mov_b32_e32 v51, v2
	v_mov_b32_e32 v52, v2
	v_mov_b32_e32 v53, v2
	v_mov_b32_e32 v54, v2
	v_mov_b32_e32 v55, v2
	v_mov_b32_e32 v56, v2
	v_mov_b32_e32 v57, v2
	v_mov_b32_e32 v10, v2
	v_mov_b32_e32 v11, v2
	v_mov_b32_e32 v12, v2
	v_mov_b32_e32 v13, v2
	v_mov_b32_e32 v14, v2
	v_mov_b32_e32 v15, v2
	v_mov_b32_e32 v16, v2
	v_mov_b32_e32 v17, v2
	v_mov_b32_e32 v26, v2
	v_mov_b32_e32 v27, v2
	v_mov_b32_e32 v28, v2
	v_mov_b32_e32 v29, v2
	v_mov_b32_e32 v30, v2
	v_mov_b32_e32 v31, v2
	v_mov_b32_e32 v32, v2
	v_mov_b32_e32 v33, v2
	v_mov_b32_e32 v42, v2
	v_mov_b32_e32 v43, v2
	v_mov_b32_e32 v44, v2
	v_mov_b32_e32 v45, v2
	v_mov_b32_e32 v46, v2
	v_mov_b32_e32 v47, v2
	v_mov_b32_e32 v48, v2
	v_mov_b32_e32 v49, v2
	v_mov_b32_e32 v58, v2
	v_mov_b32_e32 v59, v2
	v_mov_b32_e32 v60, v2
	v_mov_b32_e32 v61, v2
	v_mov_b32_e32 v62, v2
	v_mov_b32_e32 v63, v2
	v_mov_b32_e32 v64, v2
	v_mov_b32_e32 v65, v2
	v_mov_b32_e32 v66, v2
	v_mov_b32_e32 v67, v2
	v_mov_b32_e32 v68, v2
	v_mov_b32_e32 v69, v2
	v_mov_b32_e32 v70, v2
	v_mov_b32_e32 v71, v2
	v_mov_b32_e32 v72, v2
	v_mov_b32_e32 v73, v2
	v_mov_b32_e32 v82, v2
	v_mov_b32_e32 v83, v2
	v_mov_b32_e32 v84, v2
	v_mov_b32_e32 v85, v2
	v_mov_b32_e32 v86, v2
	v_mov_b32_e32 v87, v2
	v_mov_b32_e32 v88, v2
	v_mov_b32_e32 v89, v2
	v_mov_b32_e32 v98, v2
	v_mov_b32_e32 v99, v2
	v_mov_b32_e32 v100, v2
	v_mov_b32_e32 v101, v2
	v_mov_b32_e32 v102, v2
	v_mov_b32_e32 v103, v2
	v_mov_b32_e32 v104, v2
	v_mov_b32_e32 v105, v2
	v_mov_b32_e32 v114, v2
	v_mov_b32_e32 v115, v2
	v_mov_b32_e32 v116, v2
	v_mov_b32_e32 v117, v2
	v_mov_b32_e32 v118, v2
	v_mov_b32_e32 v119, v2
	v_mov_b32_e32 v120, v2
	v_mov_b32_e32 v121, v2
	v_mov_b32_e32 v74, v2
	v_mov_b32_e32 v75, v2
	v_mov_b32_e32 v76, v2
	v_mov_b32_e32 v77, v2
	v_mov_b32_e32 v78, v2
	v_mov_b32_e32 v79, v2
	v_mov_b32_e32 v80, v2
	v_mov_b32_e32 v81, v2
	v_mov_b32_e32 v90, v2
	v_mov_b32_e32 v91, v2
	v_mov_b32_e32 v92, v2
	v_mov_b32_e32 v93, v2
	v_mov_b32_e32 v94, v2
	v_mov_b32_e32 v95, v2
	v_mov_b32_e32 v96, v2
	v_mov_b32_e32 v97, v2
	v_mov_b32_e32 v106, v2
	v_mov_b32_e32 v107, v2
	v_mov_b32_e32 v108, v2
	v_mov_b32_e32 v109, v2
	v_mov_b32_e32 v110, v2
	v_mov_b32_e32 v111, v2
	v_mov_b32_e32 v112, v2
	v_mov_b32_e32 v113, v2
	v_mov_b32_e32 v122, v2
	v_mov_b32_e32 v123, v2
	v_mov_b32_e32 v124, v2
	v_mov_b32_e32 v125, v2
	v_mov_b32_e32 v126, v2
	v_mov_b32_e32 v127, v2
	v_mov_b32_e32 v128, v2
	v_mov_b32_e32 v129, v2
	.p2align	6

; DI unsigned cvt_pk_bf16(float lo, float hi) { const f32x2_t v = {lo, hi}; const bf16v2_t b = __builtin_convertvector(v, bf16v2_t); return __builtin_bit_cast(unsigned, b); }
; #define MFMA32(a, b, c) __builtin_amdgcn_mfma_f32_32x32x16_bf16((a), (b), (c), 0, 0, 0)
; DI void phase_scan(int wid0, const Params& p, unsigned char* lds, bool dry) {
;     ...
;             {
; #pragma unroll
;                 for (int g4 = 0; g4 < 4; ++g4) {
; #pragma unroll
;                     for (int j = 0; j < 4; ++j) { S0[4 * g4 + j] *= evv[g4][j]; S1[4 * g4 + j] *= evv[g4][j]; } }
;                 __builtin_amdgcn_sched_barrier(0);
; #pragma unroll
;                 for (int s = 0; s < 4; ++s) {
;                     S0 = MFMA32(kt[s], PK8(ul0[s], uh0[s]), S0);
;                     S1 = MFMA32(kt[s], PK8(ul1[s], uh1[s]), S1);
;                 }
;                 bf16_t* wp = sbt + (cur ^ 1) * 16896 + r32 * 264 + 32 * wave + 4 * hi;
; #pragma unroll
;                 for (int g4 = 0; g4 < 4; ++g4) {
;                     u32x2 w0; w0.x = cvt_pk_bf16(S0[4 * g4], S0[4 * g4 + 1]); w0.y = cvt_pk_bf16(S0[4 * g4 + 2], S0[4 * g4 + 3]);
;                     u32x2 w1; w1.x = cvt_pk_bf16(S1[4 * g4], S1[4 * g4 + 1]); w1.y = cvt_pk_bf16(S1[4 * g4 + 2], S1[4 * g4 + 3]);
;                     *(u32x2*)(wp + 8 * g4) = w0; *(u32x2*)(wp + 32 * 264 + 8 * g4) = w1;
;                 }
.LBB0_238:
	s_or_b64 exec, exec, s[6:7]
	s_waitcnt vmcnt(1)
	v_pk_mul_f32 v[16:17], v[16:17], 0 op_sel_hi:[1,0]
	v_pk_mul_f32 v[12:13], v[12:13], 0 op_sel_hi:[1,0]
	v_pk_mul_f32 v[8:9], v[8:9], 0 op_sel_hi:[1,0]
	v_pk_mul_f32 v[4:5], v[4:5], 0 op_sel_hi:[1,0]
	v_pk_mul_f32 v[14:15], v[14:15], 0 op_sel_hi:[1,0]
	v_pk_mul_f32 v[10:11], v[10:11], 0 op_sel_hi:[1,0]
	v_pk_mul_f32 v[6:7], v[6:7], 0 op_sel_hi:[1,0]
	v_pk_mul_f32 v[2:3], v[2:3], 0 op_sel_hi:[1,0]
	s_nop 1
	v_mfma_f32_32x32x16_bf16 v[18:33], v[50:53], v[90:93], v[2:17]
	v_add_u32_e32 v0, 0x8000, v131
	s_lshl_b32 s2, s11, 8
	v_add_u32_e32 v193, s15, v192
	s_or_b32 s6, s2, s10
	v_add_u32_e32 v194, s15, v130
	v_add_u32_e32 v195, s15, v144
	s_mov_b32 s2, 1
	v_mfma_f32_32x32x16_bf16 v[2:17], v[50:53], v[82:85], v[2:17]
	s_mov_b32 s8, 0
	v_lshlrev_b32_e32 v178, 1, v72
	v_mfma_f32_32x32x16_bf16 v[18:33], v[46:49], v[86:89], v[18:33]
	v_mfma_f32_32x32x16_bf16 v[2:17], v[46:49], v[78:81], v[2:17]
	v_add_u32_e32 v46, 0xc000, v131
	s_waitcnt lgkmcnt(6)
	v_mfma_f32_32x32x16_bf16 v[18:33], v[42:45], v[62:65], v[18:33]
	s_waitcnt lgkmcnt(4)
	v_mfma_f32_32x32x16_bf16 v[2:17], v[42:45], v[58:61], v[2:17]
	s_waitcnt lgkmcnt(2)
	v_mfma_f32_32x32x16_bf16 v[18:33], v[38:41], v[66:69], v[18:33]
	s_waitcnt lgkmcnt(0)
	v_mfma_f32_32x32x16_bf16 v[2:17], v[38:41], v[54:57], v[2:17]
	s_nop 9
	v_cvt_pk_bf16_f32 v42, v18, v19
	v_cvt_pk_bf16_f32 v43, v20, v21
	v_cvt_pk_bf16_f32 v40, v22, v23
	v_cvt_pk_bf16_f32 v41, v24, v25
	ds_write2_b64 v0, v[42:43], v[40:41] offset0:128 offset1:130
	v_cvt_pk_bf16_f32 v42, v30, v31
	v_cvt_pk_bf16_f32 v43, v32, v33
	v_cvt_pk_bf16_f32 v38, v2, v3
	v_cvt_pk_bf16_f32 v39, v4, v5
	v_cvt_pk_bf16_f32 v44, v6, v7
	v_cvt_pk_bf16_f32 v45, v8, v9
	ds_write2_b64 v46, v[38:39], v[44:45] offset0:192 offset1:194
	v_cvt_pk_bf16_f32 v38, v26, v27
	v_cvt_pk_bf16_f32 v39, v28, v29
	v_cvt_pk_bf16_f32 v40, v10, v11
	v_cvt_pk_bf16_f32 v41, v12, v13
	v_cvt_pk_bf16_f32 v44, v14, v15
	v_cvt_pk_bf16_f32 v45, v16, v17
	ds_write2_b64 v0, v[38:39], v[42:43] offset0:132 offset1:134
	ds_write2_b64 v46, v[40:41], v[44:45] offset0:196 offset1:198
	v_lshlrev_b32_e32 v0, 1, v70
	s_branch .LBB0_240
	.p2align	6

; #define PG8_LDA(dst, b, h) do { _Pragma("unroll") for (int m = 0; m < 4; ++m) _Pragma("unroll") for (int k = 0; k < 2; ++k) dst[m][k] = *(const LAS bf16x8*)(lds + PG8_SA(b, h) + aoff + m * 2048 + k * 1024); } while (0)
; template <class Epi>
; DI void gemm_phase(int wid0, LAS unsigned char* lds, const Gemm g, const StaticOrder& S, const Epi& E) {
;     ...
;         const bool has_next = S.next(ui + 1, nxt);
;         const char* nA = has_next ? (const char*)g.A + (size_t)nxt.pm * tstep : cA; const char* nB = has_next ? (const char*)g.Bt + (size_t)nxt.pn * tstep : cB;
;         for (int t = 0; t < nt; t += 2) {
;             const bool last = (t == nt - 2);
;             const char* a1 = cA + (size_t)(t + 1) * kstep;
;             const char* a2 = last ? nA : cA + (size_t)(t + 2) * kstep; const char* b2 = last ? nB : cB + (size_t)(t + 2) * kstep;
;             const char* a3 = a2 + kstep; const char* b3 = b2 + kstep;
;             PG8_LDB(B0, 0, 0); PG8_LDB(B1, 0, 1); PG8_SCHED; PG8_LDA(At, 0, 0); PG8_STAGE(PG8_SA(1, 1), a1 + hstep, voffA);
;             PG8_WAIT_V(8); PG8_WAIT_L(0); PG8_BAR; PG8_MMA(0, 0, At, B0); PG8_MMA(0, 1, At, B1); PG8_BAR; PG8_SCHED;
;             PG8_LDA(At, 0, 1); PG8_STAGE(PG8_SB(0, 0), b2, voffB); PG8_STAGE(PG8_SB(0, 1), b2 + hstep, voffB); PG8_STAGE(PG8_SA(0, 0), a2, voffA);
;             PG8_WAIT_V(8); PG8_WAIT_L(0); PG8_BAR; PG8_MMA(1, 0, At, B0); PG8_MMA(1, 1, At, B1); PG8_BAR; PG8_SCHED;
;             PG8_LDB(B0, 1, 0); PG8_LDB(B1, 1, 1); PG8_SCHED; PG8_LDA(At, 1, 0); PG8_STAGE(PG8_SA(0, 1), a2 + hstep, voffA);
;             PG8_WAIT_V(8); PG8_WAIT_L(0); PG8_BAR; PG8_MMA(0, 0, At, B0); PG8_MMA(0, 1, At, B1); PG8_BAR; PG8_SCHED;
;             PG8_LDA(At, 1, 1); PG8_STAGE(PG8_SB(1, 0), b3, voffB); PG8_STAGE(PG8_SB(1, 1), b3 + hstep, voffB); PG8_STAGE(PG8_SA(1, 0), a3, voffA);
;             PG8_WAIT_V(8); PG8_WAIT_L(0); PG8_BAR; PG8_MMA(1, 0, At, B0); PG8_MMA(1, 1, At, B1); PG8_BAR; PG8_SCHED;
;         }
;         if (wr == 0) PG8_BAR;
;         E(acc, cur, wr, wc, fr, fq);
;         if (!has_next) break;
; #pragma unroll
;         for (int a = 0; a < 2; ++a)
; #pragma unroll
;             for (int b = 0; b < 2; ++b)
; #pragma unroll
;                 for (int m = 0; m < 4; ++m)
; #pragma unroll
;                     for (int n = 0; n < 2; ++n) acc[a][b][m][n] = (f32x4){0.f, 0.f, 0.f, 0.f};
;         cur = nxt; cA = nA; cB = nB; ++ui;
.LBB0_276:
	s_ashr_i32 s19, s18, 31
	s_lshl_b64 s[10:11], s[18:19], 19
	s_add_u32 s20, s42, s10
	s_addc_u32 s21, s43, s11
	s_and_b64 s[10:11], s[4:5], exec
	s_cselect_b32 s7, s21, s29
	s_cselect_b32 s9, s20, s28
	s_ashr_i32 s17, s16, 31
	s_lshl_b64 s[10:11], s[16:17], 19
	s_add_u32 s22, s66, s10
	s_addc_u32 s23, s67, s11
	s_and_b64 s[10:11], s[4:5], exec
	s_cselect_b32 s10, s23, s39
	s_cselect_b32 s11, s22, s38
	s_add_u32 s28, s28, 0x40080
	s_addc_u32 s29, s29, 0
	s_add_u32 s17, s38, 0x100
	v_mov_b32_e32 v2, 0
	s_addc_u32 s19, s39, 0
	s_mov_b32 s51, -2
	v_mov_b32_e32 v3, v2
	v_mov_b32_e32 v4, v2
	v_mov_b32_e32 v5, v2
	v_mov_b32_e32 v6, v2
	v_mov_b32_e32 v7, v2
	v_mov_b32_e32 v8, v2
	v_mov_b32_e32 v9, v2
	v_mov_b32_e32 v18, v2
	v_mov_b32_e32 v19, v2
	v_mov_b32_e32 v20, v2
	v_mov_b32_e32 v21, v2
	v_mov_b32_e32 v22, v2
	v_mov_b32_e32 v23, v2
	v_mov_b32_e32 v24, v2
	v_mov_b32_e32 v25, v2
	v_mov_b32_e32 v34, v2
	v_mov_b32_e32 v35, v2
	v_mov_b32_e32 v36, v2
	v_mov_b32_e32 v37, v2
	v_mov_b32_e32 v38, v2
	v_mov_b32_e32 v39, v2
	v_mov_b32_e32 v40, v2
	v_mov_b32_e32 v41, v2
	v_mov_b32_e32 v50, v2
	v_mov_b32_e32 v51, v2
	v_mov_b32_e32 v52, v2
	v_mov_b32_e32 v53, v2
	v_mov_b32_e32 v54, v2
	v_mov_b32_e32 v55, v2
	v_mov_b32_e32 v56, v2
	v_mov_b32_e32 v57, v2
	v_mov_b32_e32 v10, v2
	v_mov_b32_e32 v11, v2
	v_mov_b32_e32 v12, v2
	v_mov_b32_e32 v13, v2
	v_mov_b32_e32 v14, v2
	v_mov_b32_e32 v15, v2
	v_mov_b32_e32 v16, v2
	v_mov_b32_e32 v17, v2
	v_mov_b32_e32 v26, v2
	v_mov_b32_e32 v27, v2
	v_mov_b32_e32 v28, v2
	v_mov_b32_e32 v29, v2
	v_mov_b32_e32 v30, v2
	v_mov_b32_e32 v31, v2
	v_mov_b32_e32 v32, v2
	v_mov_b32_e32 v33, v2
	v_mov_b32_e32 v42, v2
	v_mov_b32_e32 v43, v2
	v_mov_b32_e32 v44, v2
	v_mov_b32_e32 v45, v2
	v_mov_b32_e32 v46, v2
	v_mov_b32_e32 v47, v2
	v_mov_b32_e32 v48, v2
	v_mov_b32_e32 v49, v2
	v_mov_b32_e32 v58, v2
	v_mov_b32_e32 v59, v2
	v_mov_b32_e32 v60, v2
	v_mov_b32_e32 v61, v2
	v_mov_b32_e32 v62, v2
	v_mov_b32_e32 v63, v2
	v_mov_b32_e32 v64, v2
	v_mov_b32_e32 v65, v2
	v_mov_b32_e32 v66, v2
	v_mov_b32_e32 v67, v2
	v_mov_b32_e32 v68, v2
	v_mov_b32_e32 v69, v2
	v_mov_b32_e32 v70, v2
	v_mov_b32_e32 v71, v2
	v_mov_b32_e32 v72, v2
	v_mov_b32_e32 v73, v2
	v_mov_b32_e32 v82, v2
	v_mov_b32_e32 v83, v2
	v_mov_b32_e32 v84, v2
	v_mov_b32_e32 v85, v2
	v_mov_b32_e32 v86, v2
	v_mov_b32_e32 v87, v2
	v_mov_b32_e32 v88, v2
	v_mov_b32_e32 v89, v2
	v_mov_b32_e32 v98, v2
	v_mov_b32_e32 v99, v2
	v_mov_b32_e32 v100, v2
	v_mov_b32_e32 v101, v2
	v_mov_b32_e32 v102, v2
	v_mov_b32_e32 v103, v2
	v_mov_b32_e32 v104, v2
	v_mov_b32_e32 v105, v2
	v_mov_b32_e32 v114, v2
	v_mov_b32_e32 v115, v2
	v_mov_b32_e32 v116, v2
	v_mov_b32_e32 v117, v2
	v_mov_b32_e32 v118, v2
	v_mov_b32_e32 v119, v2
	v_mov_b32_e32 v120, v2
	v_mov_b32_e32 v121, v2
	v_mov_b32_e32 v74, v2
	v_mov_b32_e32 v75, v2
	v_mov_b32_e32 v76, v2
	v_mov_b32_e32 v77, v2
	v_mov_b32_e32 v78, v2
	v_mov_b32_e32 v79, v2
	v_mov_b32_e32 v80, v2
	v_mov_b32_e32 v81, v2
	v_mov_b32_e32 v90, v2
	v_mov_b32_e32 v91, v2
	v_mov_b32_e32 v92, v2
	v_mov_b32_e32 v93, v2
	v_mov_b32_e32 v94, v2
	v_mov_b32_e32 v95, v2
	v_mov_b32_e32 v96, v2
	v_mov_b32_e32 v97, v2
	v_mov_b32_e32 v106, v2
	v_mov_b32_e32 v107, v2
	v_mov_b32_e32 v108, v2
	v_mov_b32_e32 v109, v2
	v_mov_b32_e32 v110, v2
	v_mov_b32_e32 v111, v2
	v_mov_b32_e32 v112, v2
	v_mov_b32_e32 v113, v2
	v_mov_b32_e32 v122, v2
	v_mov_b32_e32 v123, v2
	v_mov_b32_e32 v124, v2
	v_mov_b32_e32 v125, v2
	v_mov_b32_e32 v126, v2
	v_mov_b32_e32 v127, v2
	v_mov_b32_e32 v128, v2
	v_mov_b32_e32 v129, v2
	.p2align	6
